# GEMM K-loops: loop bookkeeping issued before the loop-end barrier, only the back-edge branch behind it
# speedup vs baseline: 1.0216x; 1.0021x over previous
.LBB0_126:
	ds_read_b128 v[148:151], v159
	ds_read_b128 v[152:155], v159 offset:1024
	ds_read_b128 v[162:165], v159 offset:2048
	ds_read_b128 v[166:169], v159 offset:3072
	ds_read_b128 v[170:173], v160
	ds_read_b128 v[174:177], v160 offset:1024
	ds_read_b128 v[178:181], v160 offset:2048
	ds_read_b128 v[182:185], v160 offset:3072
	s_add_u32 s34, s30, 0xfffc0080
	s_addc_u32 s35, s31, -1
	s_cmp_eq_u32 s72, 12
	s_cselect_b32 s37, s5, s35
	s_cselect_b32 s36, s38, s34
	s_cselect_b32 s35, s39, s71
	s_cselect_b32 s34, s44, s45
	v_lshl_add_u64 v[156:157], s[30:31], 0, v[140:141]
	s_add_i32 m0, s48, 0xc000
	ds_read_b128 v[186:189], v161
	ds_read_b128 v[190:193], v161 offset:1024
	ds_read_b128 v[194:197], v161 offset:2048
	ds_read_b128 v[198:201], v161 offset:3072
	ds_read_b128 v[202:205], v161 offset:4096
	ds_read_b128 v[206:209], v161 offset:5120
	ds_read_b128 v[210:213], v161 offset:6144
	ds_read_b128 v[214:217], v161 offset:7168
	global_load_lds_dwordx4 v[156:157], off
	v_lshl_add_u64 v[156:157], s[30:31], 0, v[142:143]
	s_add_i32 m0, s48, 0xe000
	s_nop 0
	global_load_lds_dwordx4 v[156:157], off
	s_waitcnt vmcnt(8)
	s_waitcnt lgkmcnt(0)
	s_barrier
	s_setprio 1
	s_waitcnt lgkmcnt(0)
	v_mfma_f32_16x16x32_bf16 v[126:129], v[148:151], v[186:189], v[126:129]
	v_mfma_f32_16x16x32_bf16 v[122:125], v[162:165], v[186:189], v[122:125]
	v_mfma_f32_16x16x32_bf16 v[110:113], v[148:151], v[194:197], v[110:113]
	v_mfma_f32_16x16x32_bf16 v[106:109], v[162:165], v[194:197], v[106:109]
	v_mfma_f32_16x16x32_bf16 v[94:97], v[148:151], v[202:205], v[94:97]
	v_mfma_f32_16x16x32_bf16 v[90:93], v[162:165], v[202:205], v[90:93]
	v_mfma_f32_16x16x32_bf16 v[78:81], v[148:151], v[210:213], v[78:81]
	v_mfma_f32_16x16x32_bf16 v[74:77], v[162:165], v[210:213], v[74:77]
	v_mfma_f32_16x16x32_bf16 v[126:129], v[152:155], v[190:193], v[126:129]
	v_mfma_f32_16x16x32_bf16 v[122:125], v[166:169], v[190:193], v[122:125]
	v_mfma_f32_16x16x32_bf16 v[110:113], v[152:155], v[198:201], v[110:113]
	v_mfma_f32_16x16x32_bf16 v[106:109], v[166:169], v[198:201], v[106:109]
	v_mfma_f32_16x16x32_bf16 v[94:97], v[152:155], v[206:209], v[94:97]
	v_mfma_f32_16x16x32_bf16 v[90:93], v[166:169], v[206:209], v[90:93]
	v_mfma_f32_16x16x32_bf16 v[78:81], v[152:155], v[214:217], v[78:81]
	v_mfma_f32_16x16x32_bf16 v[74:77], v[166:169], v[214:217], v[74:77]
	s_setprio 0
	s_setprio 1
	v_mfma_f32_16x16x32_bf16 v[118:121], v[170:173], v[186:189], v[118:121]
	v_mfma_f32_16x16x32_bf16 v[114:117], v[178:181], v[186:189], v[114:117]
	v_mfma_f32_16x16x32_bf16 v[102:105], v[170:173], v[194:197], v[102:105]
	v_mfma_f32_16x16x32_bf16 v[98:101], v[178:181], v[194:197], v[98:101]
	v_mfma_f32_16x16x32_bf16 v[86:89], v[170:173], v[202:205], v[86:89]
	v_mfma_f32_16x16x32_bf16 v[82:85], v[178:181], v[202:205], v[82:85]
	v_mfma_f32_16x16x32_bf16 v[70:73], v[170:173], v[210:213], v[70:73]
	v_mfma_f32_16x16x32_bf16 v[66:69], v[178:181], v[210:213], v[66:69]
	v_mfma_f32_16x16x32_bf16 v[118:121], v[174:177], v[190:193], v[118:121]
	v_mfma_f32_16x16x32_bf16 v[114:117], v[182:185], v[190:193], v[114:117]
	v_mfma_f32_16x16x32_bf16 v[102:105], v[174:177], v[198:201], v[102:105]
	v_mfma_f32_16x16x32_bf16 v[98:101], v[182:185], v[198:201], v[98:101]
	v_mfma_f32_16x16x32_bf16 v[86:89], v[174:177], v[206:209], v[86:89]
	v_mfma_f32_16x16x32_bf16 v[82:85], v[182:185], v[206:209], v[82:85]
	v_mfma_f32_16x16x32_bf16 v[70:73], v[174:177], v[214:217], v[70:73]
	v_mfma_f32_16x16x32_bf16 v[66:69], v[182:185], v[214:217], v[66:69]
	s_setprio 0
	s_barrier
	s_add_i32 s73, s65, s47
	v_lshl_add_u64 v[156:157], s[34:35], 0, v[132:133]
	s_mov_b32 m0, s73
	ds_read_b128 v[186:189], v161 offset:16384
	ds_read_b128 v[190:193], v161 offset:17408
	ds_read_b128 v[194:197], v161 offset:18432
	ds_read_b128 v[198:201], v161 offset:19456
	ds_read_b128 v[202:205], v161 offset:20480
	ds_read_b128 v[206:209], v161 offset:21504
	ds_read_b128 v[210:213], v161 offset:22528
	ds_read_b128 v[214:217], v161 offset:23552
	global_load_lds_dwordx4 v[156:157], off
	s_add_i32 m0, s73, 0x2000
	s_add_u32 s74, s34, 0x40000
	v_lshl_add_u64 v[218:219], s[34:35], 0, v[136:137]
	s_addc_u32 s75, s35, 0
	s_add_i32 s73, s66, s47
	global_load_lds_dwordx4 v[218:219], off
	v_lshl_add_u64 v[220:221], s[74:75], 0, v[132:133]
	s_mov_b32 m0, s73
	v_lshl_add_u64 v[222:223], s[36:37], 0, v[134:135]
	global_load_lds_dwordx4 v[220:221], off
	v_lshl_add_u64 v[220:221], s[74:75], 0, v[136:137]
	s_add_i32 m0, s73, 0x2000
	s_nop 0
	global_load_lds_dwordx4 v[220:221], off
	v_lshl_add_u64 v[220:221], s[36:37], 0, v[130:131]
	s_mov_b32 m0, s48
	s_nop 0
	global_load_lds_dwordx4 v[220:221], off
	s_mov_b32 m0, s49
	s_nop 0
	global_load_lds_dwordx4 v[222:223], off
	s_waitcnt vmcnt(8)
	s_waitcnt lgkmcnt(0)
	s_barrier
	s_setprio 1
	s_waitcnt lgkmcnt(0)
	v_mfma_f32_16x16x32_bf16 v[62:65], v[148:151], v[186:189], v[62:65]
	v_mfma_f32_16x16x32_bf16 v[58:61], v[162:165], v[186:189], v[58:61]
	v_mfma_f32_16x16x32_bf16 v[46:49], v[148:151], v[194:197], v[46:49]
	v_mfma_f32_16x16x32_bf16 v[42:45], v[162:165], v[194:197], v[42:45]
	v_mfma_f32_16x16x32_bf16 v[30:33], v[148:151], v[202:205], v[30:33]
	v_mfma_f32_16x16x32_bf16 v[26:29], v[162:165], v[202:205], v[26:29]
	v_mfma_f32_16x16x32_bf16 v[14:17], v[148:151], v[210:213], v[14:17]
	v_mfma_f32_16x16x32_bf16 v[10:13], v[162:165], v[210:213], v[10:13]
	v_mfma_f32_16x16x32_bf16 v[62:65], v[152:155], v[190:193], v[62:65]
	v_mfma_f32_16x16x32_bf16 v[58:61], v[166:169], v[190:193], v[58:61]
	v_mfma_f32_16x16x32_bf16 v[46:49], v[152:155], v[198:201], v[46:49]
	v_mfma_f32_16x16x32_bf16 v[42:45], v[166:169], v[198:201], v[42:45]
	v_mfma_f32_16x16x32_bf16 v[30:33], v[152:155], v[206:209], v[30:33]
	v_mfma_f32_16x16x32_bf16 v[26:29], v[166:169], v[206:209], v[26:29]
	v_mfma_f32_16x16x32_bf16 v[14:17], v[152:155], v[214:217], v[14:17]
	v_mfma_f32_16x16x32_bf16 v[10:13], v[166:169], v[214:217], v[10:13]
	s_setprio 0
	s_setprio 1
	v_mfma_f32_16x16x32_bf16 v[54:57], v[170:173], v[186:189], v[54:57]
	v_mfma_f32_16x16x32_bf16 v[50:53], v[178:181], v[186:189], v[50:53]
	v_mfma_f32_16x16x32_bf16 v[38:41], v[170:173], v[194:197], v[38:41]
	v_mfma_f32_16x16x32_bf16 v[34:37], v[178:181], v[194:197], v[34:37]
	v_mfma_f32_16x16x32_bf16 v[22:25], v[170:173], v[202:205], v[22:25]
	v_mfma_f32_16x16x32_bf16 v[18:21], v[178:181], v[202:205], v[18:21]
	v_mfma_f32_16x16x32_bf16 v[6:9], v[170:173], v[210:213], v[6:9]
	v_mfma_f32_16x16x32_bf16 v[2:5], v[178:181], v[210:213], v[2:5]
	v_mfma_f32_16x16x32_bf16 v[54:57], v[174:177], v[190:193], v[54:57]
	v_mfma_f32_16x16x32_bf16 v[50:53], v[182:185], v[190:193], v[50:53]
	v_mfma_f32_16x16x32_bf16 v[38:41], v[174:177], v[198:201], v[38:41]
	v_mfma_f32_16x16x32_bf16 v[34:37], v[182:185], v[198:201], v[34:37]
	v_mfma_f32_16x16x32_bf16 v[22:25], v[174:177], v[206:209], v[22:25]
	v_mfma_f32_16x16x32_bf16 v[18:21], v[182:185], v[206:209], v[18:21]
	v_mfma_f32_16x16x32_bf16 v[6:9], v[174:177], v[214:217], v[6:9]
	v_mfma_f32_16x16x32_bf16 v[2:5], v[182:185], v[214:217], v[2:5]
	s_setprio 0
	s_barrier
	s_add_i32 s73, 0, 0x18000
	v_add_u32_e32 v138, s73, v158
	s_add_i32 s74, 0, 0x1c000
	ds_read_b128 v[148:151], v138
	ds_read_b128 v[152:155], v138 offset:1024
	ds_read_b128 v[162:165], v138 offset:2048
	ds_read_b128 v[166:169], v138 offset:3072
	v_add_u32_e32 v138, s74, v158
	ds_read_b128 v[170:173], v138
	ds_read_b128 v[174:177], v138 offset:1024
	ds_read_b128 v[178:181], v138 offset:2048
	ds_read_b128 v[182:185], v138 offset:3072
	s_add_u32 s36, s36, 0x40000
	s_addc_u32 s37, s37, 0
	s_mov_b32 m0, s50
	v_lshl_add_u64 v[224:225], s[36:37], 0, v[130:131]
	ds_read_b128 v[186:189], v161 offset:32768
	ds_read_b128 v[190:193], v161 offset:33792
	ds_read_b128 v[194:197], v161 offset:34816
	ds_read_b128 v[198:201], v161 offset:35840
	ds_read_b128 v[202:205], v161 offset:36864
	ds_read_b128 v[206:209], v161 offset:37888
	ds_read_b128 v[210:213], v161 offset:38912
	ds_read_b128 v[214:217], v161 offset:39936
	global_load_lds_dwordx4 v[224:225], off
	v_lshl_add_u64 v[224:225], s[36:37], 0, v[134:135]
	s_mov_b32 m0, s51
	s_nop 0
	global_load_lds_dwordx4 v[224:225], off
	s_waitcnt vmcnt(8)
	s_waitcnt lgkmcnt(0)
	s_barrier
	s_setprio 1
	s_waitcnt lgkmcnt(0)
	v_mfma_f32_16x16x32_bf16 v[126:129], v[148:151], v[186:189], v[126:129]
	v_mfma_f32_16x16x32_bf16 v[122:125], v[162:165], v[186:189], v[122:125]
	v_mfma_f32_16x16x32_bf16 v[110:113], v[148:151], v[194:197], v[110:113]
	v_mfma_f32_16x16x32_bf16 v[106:109], v[162:165], v[194:197], v[106:109]
	v_mfma_f32_16x16x32_bf16 v[94:97], v[148:151], v[202:205], v[94:97]
	v_mfma_f32_16x16x32_bf16 v[90:93], v[162:165], v[202:205], v[90:93]
	v_mfma_f32_16x16x32_bf16 v[78:81], v[148:151], v[210:213], v[78:81]
	v_mfma_f32_16x16x32_bf16 v[74:77], v[162:165], v[210:213], v[74:77]
	v_mfma_f32_16x16x32_bf16 v[126:129], v[152:155], v[190:193], v[126:129]
	v_mfma_f32_16x16x32_bf16 v[122:125], v[166:169], v[190:193], v[122:125]
	v_mfma_f32_16x16x32_bf16 v[110:113], v[152:155], v[198:201], v[110:113]
	v_mfma_f32_16x16x32_bf16 v[106:109], v[166:169], v[198:201], v[106:109]
	v_mfma_f32_16x16x32_bf16 v[94:97], v[152:155], v[206:209], v[94:97]
	v_mfma_f32_16x16x32_bf16 v[90:93], v[166:169], v[206:209], v[90:93]
	v_mfma_f32_16x16x32_bf16 v[78:81], v[152:155], v[214:217], v[78:81]
	v_mfma_f32_16x16x32_bf16 v[74:77], v[166:169], v[214:217], v[74:77]
	s_setprio 0
	s_setprio 1
	v_mfma_f32_16x16x32_bf16 v[118:121], v[170:173], v[186:189], v[118:121]
	v_mfma_f32_16x16x32_bf16 v[114:117], v[178:181], v[186:189], v[114:117]
	v_mfma_f32_16x16x32_bf16 v[102:105], v[170:173], v[194:197], v[102:105]
	v_mfma_f32_16x16x32_bf16 v[98:101], v[178:181], v[194:197], v[98:101]
	v_mfma_f32_16x16x32_bf16 v[86:89], v[170:173], v[202:205], v[86:89]
	v_mfma_f32_16x16x32_bf16 v[82:85], v[178:181], v[202:205], v[82:85]
	v_mfma_f32_16x16x32_bf16 v[70:73], v[170:173], v[210:213], v[70:73]
	v_mfma_f32_16x16x32_bf16 v[66:69], v[178:181], v[210:213], v[66:69]
	v_mfma_f32_16x16x32_bf16 v[118:121], v[174:177], v[190:193], v[118:121]
	v_mfma_f32_16x16x32_bf16 v[114:117], v[182:185], v[190:193], v[114:117]
	v_mfma_f32_16x16x32_bf16 v[102:105], v[174:177], v[198:201], v[102:105]
	v_mfma_f32_16x16x32_bf16 v[98:101], v[182:185], v[198:201], v[98:101]
	v_mfma_f32_16x16x32_bf16 v[86:89], v[174:177], v[206:209], v[86:89]
	v_mfma_f32_16x16x32_bf16 v[82:85], v[182:185], v[206:209], v[82:85]
	v_mfma_f32_16x16x32_bf16 v[70:73], v[174:177], v[214:217], v[70:73]
	v_mfma_f32_16x16x32_bf16 v[66:69], v[182:185], v[214:217], v[66:69]
	s_setprio 0
	s_barrier
	s_add_i32 s36, s73, s47
	v_lshl_add_u64 v[156:157], v[156:157], 0, s[14:15]
	s_mov_b32 m0, s36
	ds_read_b128 v[186:189], v161 offset:49152
	ds_read_b128 v[190:193], v161 offset:50176
	ds_read_b128 v[194:197], v161 offset:51200
	ds_read_b128 v[198:201], v161 offset:52224
	ds_read_b128 v[202:205], v161 offset:53248
	ds_read_b128 v[206:209], v161 offset:54272
	ds_read_b128 v[210:213], v161 offset:55296
	ds_read_b128 v[214:217], v161 offset:56320
	global_load_lds_dwordx4 v[156:157], off
	s_add_i32 m0, s36, 0x2000
	s_add_u32 s34, s34, 0x40080
	v_lshl_add_u64 v[156:157], v[218:219], 0, s[14:15]
	s_addc_u32 s35, s35, 0
	s_add_i32 s36, s74, s47
	global_load_lds_dwordx4 v[156:157], off
	v_lshl_add_u64 v[156:157], s[34:35], 0, v[132:133]
	s_mov_b32 m0, s36
	s_nop 0
	global_load_lds_dwordx4 v[156:157], off
	v_lshl_add_u64 v[156:157], s[34:35], 0, v[136:137]
	s_add_i32 m0, s36, 0x2000
	s_nop 0
	global_load_lds_dwordx4 v[156:157], off
	v_lshl_add_u64 v[156:157], v[220:221], 0, s[14:15]
	s_mov_b32 m0, s62
	s_nop 0
	global_load_lds_dwordx4 v[156:157], off
	v_lshl_add_u64 v[156:157], v[222:223], 0, s[14:15]
	s_mov_b32 m0, s63
	s_nop 0
	global_load_lds_dwordx4 v[156:157], off
	s_waitcnt vmcnt(8)
	s_waitcnt lgkmcnt(0)
	s_barrier
	s_setprio 1
	s_waitcnt lgkmcnt(0)
	v_mfma_f32_16x16x32_bf16 v[62:65], v[148:151], v[186:189], v[62:65]
	v_mfma_f32_16x16x32_bf16 v[58:61], v[162:165], v[186:189], v[58:61]
	v_mfma_f32_16x16x32_bf16 v[46:49], v[148:151], v[194:197], v[46:49]
	v_mfma_f32_16x16x32_bf16 v[42:45], v[162:165], v[194:197], v[42:45]
	v_mfma_f32_16x16x32_bf16 v[30:33], v[148:151], v[202:205], v[30:33]
	v_mfma_f32_16x16x32_bf16 v[26:29], v[162:165], v[202:205], v[26:29]
	v_mfma_f32_16x16x32_bf16 v[14:17], v[148:151], v[210:213], v[14:17]
	v_mfma_f32_16x16x32_bf16 v[10:13], v[162:165], v[210:213], v[10:13]
	v_mfma_f32_16x16x32_bf16 v[62:65], v[152:155], v[190:193], v[62:65]
	v_mfma_f32_16x16x32_bf16 v[58:61], v[166:169], v[190:193], v[58:61]
	v_mfma_f32_16x16x32_bf16 v[46:49], v[152:155], v[198:201], v[46:49]
	v_mfma_f32_16x16x32_bf16 v[42:45], v[166:169], v[198:201], v[42:45]
	v_mfma_f32_16x16x32_bf16 v[30:33], v[152:155], v[206:209], v[30:33]
	v_mfma_f32_16x16x32_bf16 v[26:29], v[166:169], v[206:209], v[26:29]
	v_mfma_f32_16x16x32_bf16 v[14:17], v[152:155], v[214:217], v[14:17]
	v_mfma_f32_16x16x32_bf16 v[10:13], v[166:169], v[214:217], v[10:13]
	s_setprio 0
	s_setprio 1
	v_mfma_f32_16x16x32_bf16 v[54:57], v[170:173], v[186:189], v[54:57]
	v_mfma_f32_16x16x32_bf16 v[50:53], v[178:181], v[186:189], v[50:53]
	v_mfma_f32_16x16x32_bf16 v[38:41], v[170:173], v[194:197], v[38:41]
	v_mfma_f32_16x16x32_bf16 v[34:37], v[178:181], v[194:197], v[34:37]
	v_mfma_f32_16x16x32_bf16 v[22:25], v[170:173], v[202:205], v[22:25]
	v_mfma_f32_16x16x32_bf16 v[18:21], v[178:181], v[202:205], v[18:21]
	v_mfma_f32_16x16x32_bf16 v[6:9], v[170:173], v[210:213], v[6:9]
	v_mfma_f32_16x16x32_bf16 v[2:5], v[178:181], v[210:213], v[2:5]
	v_mfma_f32_16x16x32_bf16 v[54:57], v[174:177], v[190:193], v[54:57]
	v_mfma_f32_16x16x32_bf16 v[50:53], v[182:185], v[190:193], v[50:53]
	v_mfma_f32_16x16x32_bf16 v[38:41], v[174:177], v[198:201], v[38:41]
	v_mfma_f32_16x16x32_bf16 v[34:37], v[182:185], v[198:201], v[34:37]
	v_mfma_f32_16x16x32_bf16 v[22:25], v[174:177], v[206:209], v[22:25]
	v_mfma_f32_16x16x32_bf16 v[18:21], v[182:185], v[206:209], v[18:21]
	v_mfma_f32_16x16x32_bf16 v[6:9], v[174:177], v[214:217], v[6:9]
	v_mfma_f32_16x16x32_bf16 v[2:5], v[182:185], v[214:217], v[2:5]
	s_setprio 0
	s_add_i32 s72, s72, 2
	s_add_u32 s30, s30, 0x100
	s_addc_u32 s31, s31, 0
	s_add_u32 s45, s45, 0x100
	s_addc_u32 s71, s71, 0
	s_cmp_gt_u32 s72, 13
	s_barrier
	s_cbranch_scc0 .LBB0_126
	s_and_b64 vcc, exec, s[18:19]
	s_cbranch_vccz .LBB0_129
	s_barrier

.LBB0_761:
	v_add_u32_e32 v164, s62, v150
	v_add_u32_e32 v180, s63, v150
	s_add_u32 s34, s16, s26
	ds_read_b128 v[152:155], v164
	ds_read_b128 v[156:159], v164 offset:1024
	ds_read_b128 v[160:163], v164 offset:2048
	ds_read_b128 v[164:167], v164 offset:3072
	ds_read_b128 v[168:171], v180
	ds_read_b128 v[172:175], v180 offset:1024
	ds_read_b128 v[176:179], v180 offset:2048
	ds_read_b128 v[180:183], v180 offset:3072
	s_addc_u32 s35, s17, s27
	s_add_u32 s34, s34, 0x100
	s_addc_u32 s35, s35, 0
	s_add_u32 s68, s21, s26
	s_addc_u32 s69, s66, s27
	s_cmpk_eq_i32 s26, 0xf00
	s_cselect_b32 s37, s29, s35
	s_cselect_b32 s36, s28, s34
	s_cselect_b32 s35, s31, s69
	s_cselect_b32 s34, s30, s68
	v_lshl_add_u64 v[216:217], v[146:147], 0, s[26:27]
	s_add_i32 m0, s15, 0xc000
	ds_read_b128 v[184:187], v151
	ds_read_b128 v[188:191], v151 offset:1024
	ds_read_b128 v[192:195], v151 offset:2048
	ds_read_b128 v[196:199], v151 offset:3072
	ds_read_b128 v[200:203], v151 offset:4096
	ds_read_b128 v[204:207], v151 offset:5120
	ds_read_b128 v[208:211], v151 offset:6144
	ds_read_b128 v[212:215], v151 offset:7168
	global_load_lds_dwordx4 v[216:217], off
	v_lshl_add_u64 v[216:217], v[148:149], 0, s[26:27]
	s_add_i32 m0, s15, 0xe000
	s_nop 0
	global_load_lds_dwordx4 v[216:217], off
	s_waitcnt vmcnt(8)
	s_waitcnt lgkmcnt(0)
	s_barrier
	s_setprio 1
	s_waitcnt lgkmcnt(0)
	v_mfma_f32_16x16x32_bf16 v[126:129], v[152:155], v[184:187], v[126:129]
	v_mfma_f32_16x16x32_bf16 v[122:125], v[160:163], v[184:187], v[122:125]
	v_mfma_f32_16x16x32_bf16 v[118:121], v[152:155], v[192:195], v[118:121]
	v_mfma_f32_16x16x32_bf16 v[114:117], v[160:163], v[192:195], v[114:117]
	v_mfma_f32_16x16x32_bf16 v[94:97], v[152:155], v[200:203], v[94:97]
	v_mfma_f32_16x16x32_bf16 v[90:93], v[160:163], v[200:203], v[90:93]
	v_mfma_f32_16x16x32_bf16 v[86:89], v[152:155], v[208:211], v[86:89]
	v_mfma_f32_16x16x32_bf16 v[82:85], v[160:163], v[208:211], v[82:85]
	v_mfma_f32_16x16x32_bf16 v[126:129], v[156:159], v[188:191], v[126:129]
	v_mfma_f32_16x16x32_bf16 v[122:125], v[164:167], v[188:191], v[122:125]
	v_mfma_f32_16x16x32_bf16 v[118:121], v[156:159], v[196:199], v[118:121]
	v_mfma_f32_16x16x32_bf16 v[114:117], v[164:167], v[196:199], v[114:117]
	v_mfma_f32_16x16x32_bf16 v[94:97], v[156:159], v[204:207], v[94:97]
	v_mfma_f32_16x16x32_bf16 v[90:93], v[164:167], v[204:207], v[90:93]
	v_mfma_f32_16x16x32_bf16 v[86:89], v[156:159], v[212:215], v[86:89]
	v_mfma_f32_16x16x32_bf16 v[82:85], v[164:167], v[212:215], v[82:85]
	s_setprio 0
	s_setprio 1
	v_mfma_f32_16x16x32_bf16 v[110:113], v[168:171], v[184:187], v[110:113]
	v_mfma_f32_16x16x32_bf16 v[106:109], v[176:179], v[184:187], v[106:109]
	v_mfma_f32_16x16x32_bf16 v[102:105], v[168:171], v[192:195], v[102:105]
	v_mfma_f32_16x16x32_bf16 v[98:101], v[176:179], v[192:195], v[98:101]
	v_mfma_f32_16x16x32_bf16 v[78:81], v[168:171], v[200:203], v[78:81]
	v_mfma_f32_16x16x32_bf16 v[74:77], v[176:179], v[200:203], v[74:77]
	v_mfma_f32_16x16x32_bf16 v[70:73], v[168:171], v[208:211], v[70:73]
	v_mfma_f32_16x16x32_bf16 v[66:69], v[176:179], v[208:211], v[66:69]
	v_mfma_f32_16x16x32_bf16 v[110:113], v[172:175], v[188:191], v[110:113]
	v_mfma_f32_16x16x32_bf16 v[106:109], v[180:183], v[188:191], v[106:109]
	v_mfma_f32_16x16x32_bf16 v[102:105], v[172:175], v[196:199], v[102:105]
	v_mfma_f32_16x16x32_bf16 v[98:101], v[180:183], v[196:199], v[98:101]
	v_mfma_f32_16x16x32_bf16 v[78:81], v[172:175], v[204:207], v[78:81]
	v_mfma_f32_16x16x32_bf16 v[74:77], v[180:183], v[204:207], v[74:77]
	v_mfma_f32_16x16x32_bf16 v[70:73], v[172:175], v[212:215], v[70:73]
	v_mfma_f32_16x16x32_bf16 v[66:69], v[180:183], v[212:215], v[66:69]
	s_setprio 0
	s_barrier
	s_add_i32 s68, s62, s48
	v_lshl_add_u64 v[216:217], s[34:35], 0, v[132:133]
	s_mov_b32 m0, s68
	ds_read_b128 v[184:187], v151 offset:16384
	ds_read_b128 v[188:191], v151 offset:17408
	ds_read_b128 v[192:195], v151 offset:18432
	ds_read_b128 v[196:199], v151 offset:19456
	ds_read_b128 v[200:203], v151 offset:20480
	ds_read_b128 v[204:207], v151 offset:21504
	ds_read_b128 v[208:211], v151 offset:22528
	ds_read_b128 v[212:215], v151 offset:23552
	global_load_lds_dwordx4 v[216:217], off
	s_add_i32 m0, s68, 0x2000
	s_add_u32 s68, s34, 0x80000
	v_lshl_add_u64 v[218:219], s[34:35], 0, v[136:137]
	s_addc_u32 s69, s35, 0
	s_add_i32 s70, s63, s48
	global_load_lds_dwordx4 v[218:219], off
	v_lshl_add_u64 v[220:221], s[68:69], 0, v[132:133]
	s_mov_b32 m0, s70
	v_lshl_add_u64 v[222:223], s[36:37], 0, v[134:135]
	global_load_lds_dwordx4 v[220:221], off
	v_lshl_add_u64 v[220:221], s[68:69], 0, v[136:137]
	s_add_i32 m0, s70, 0x2000
	s_nop 0
	global_load_lds_dwordx4 v[220:221], off
	v_lshl_add_u64 v[220:221], s[36:37], 0, v[130:131]
	s_mov_b32 m0, s15
	s_nop 0
	global_load_lds_dwordx4 v[220:221], off
	s_mov_b32 m0, s50
	s_nop 0
	global_load_lds_dwordx4 v[222:223], off
	s_waitcnt vmcnt(8)
	s_waitcnt lgkmcnt(0)
	s_barrier
	s_setprio 1
	s_waitcnt lgkmcnt(0)
	v_mfma_f32_16x16x32_bf16 v[62:65], v[152:155], v[184:187], v[62:65]
	v_mfma_f32_16x16x32_bf16 v[58:61], v[160:163], v[184:187], v[58:61]
	v_mfma_f32_16x16x32_bf16 v[54:57], v[152:155], v[192:195], v[54:57]
	v_mfma_f32_16x16x32_bf16 v[50:53], v[160:163], v[192:195], v[50:53]
	v_mfma_f32_16x16x32_bf16 v[30:33], v[152:155], v[200:203], v[30:33]
	v_mfma_f32_16x16x32_bf16 v[26:29], v[160:163], v[200:203], v[26:29]
	v_mfma_f32_16x16x32_bf16 v[22:25], v[152:155], v[208:211], v[22:25]
	v_mfma_f32_16x16x32_bf16 v[18:21], v[160:163], v[208:211], v[18:21]
	v_mfma_f32_16x16x32_bf16 v[62:65], v[156:159], v[188:191], v[62:65]
	v_mfma_f32_16x16x32_bf16 v[58:61], v[164:167], v[188:191], v[58:61]
	v_mfma_f32_16x16x32_bf16 v[54:57], v[156:159], v[196:199], v[54:57]
	v_mfma_f32_16x16x32_bf16 v[50:53], v[164:167], v[196:199], v[50:53]
	v_mfma_f32_16x16x32_bf16 v[30:33], v[156:159], v[204:207], v[30:33]
	v_mfma_f32_16x16x32_bf16 v[26:29], v[164:167], v[204:207], v[26:29]
	v_mfma_f32_16x16x32_bf16 v[22:25], v[156:159], v[212:215], v[22:25]
	v_mfma_f32_16x16x32_bf16 v[18:21], v[164:167], v[212:215], v[18:21]
	s_setprio 0
	s_setprio 1
	v_mfma_f32_16x16x32_bf16 v[46:49], v[168:171], v[184:187], v[46:49]
	v_mfma_f32_16x16x32_bf16 v[42:45], v[176:179], v[184:187], v[42:45]
	v_mfma_f32_16x16x32_bf16 v[38:41], v[168:171], v[192:195], v[38:41]
	v_mfma_f32_16x16x32_bf16 v[34:37], v[176:179], v[192:195], v[34:37]
	v_mfma_f32_16x16x32_bf16 v[14:17], v[168:171], v[200:203], v[14:17]
	v_mfma_f32_16x16x32_bf16 v[10:13], v[176:179], v[200:203], v[10:13]
	v_mfma_f32_16x16x32_bf16 v[6:9], v[168:171], v[208:211], v[6:9]
	v_mfma_f32_16x16x32_bf16 v[2:5], v[176:179], v[208:211], v[2:5]
	v_mfma_f32_16x16x32_bf16 v[46:49], v[172:175], v[188:191], v[46:49]
	v_mfma_f32_16x16x32_bf16 v[42:45], v[180:183], v[188:191], v[42:45]
	v_mfma_f32_16x16x32_bf16 v[38:41], v[172:175], v[196:199], v[38:41]
	v_mfma_f32_16x16x32_bf16 v[34:37], v[180:183], v[196:199], v[34:37]
	v_mfma_f32_16x16x32_bf16 v[14:17], v[172:175], v[204:207], v[14:17]
	v_mfma_f32_16x16x32_bf16 v[10:13], v[180:183], v[204:207], v[10:13]
	v_mfma_f32_16x16x32_bf16 v[6:9], v[172:175], v[212:215], v[6:9]
	v_mfma_f32_16x16x32_bf16 v[2:5], v[180:183], v[212:215], v[2:5]
	s_setprio 0
	s_barrier
	s_add_i32 s68, 0, 0x18000
	s_add_i32 s69, 0, 0x1c000
	v_add_u32_e32 v164, s68, v150
	v_add_u32_e32 v180, s69, v150
	ds_read_b128 v[152:155], v164
	ds_read_b128 v[156:159], v164 offset:1024
	ds_read_b128 v[160:163], v164 offset:2048
	ds_read_b128 v[164:167], v164 offset:3072
	ds_read_b128 v[168:171], v180
	ds_read_b128 v[172:175], v180 offset:1024
	ds_read_b128 v[176:179], v180 offset:2048
	ds_read_b128 v[180:183], v180 offset:3072
	s_add_u32 s36, s36, 0x80000
	s_addc_u32 s37, s37, 0
	s_mov_b32 m0, s51
	v_lshl_add_u64 v[224:225], s[36:37], 0, v[130:131]
	ds_read_b128 v[184:187], v151 offset:32768
	ds_read_b128 v[188:191], v151 offset:33792
	ds_read_b128 v[192:195], v151 offset:34816
	ds_read_b128 v[196:199], v151 offset:35840
	ds_read_b128 v[200:203], v151 offset:36864
	ds_read_b128 v[204:207], v151 offset:37888
	ds_read_b128 v[208:211], v151 offset:38912
	ds_read_b128 v[212:215], v151 offset:39936
	global_load_lds_dwordx4 v[224:225], off
	v_lshl_add_u64 v[224:225], s[36:37], 0, v[134:135]
	s_mov_b32 m0, s57
	s_nop 0
	global_load_lds_dwordx4 v[224:225], off
	s_waitcnt vmcnt(8)
	s_waitcnt lgkmcnt(0)
	s_barrier
	s_setprio 1
	s_waitcnt lgkmcnt(0)
	v_mfma_f32_16x16x32_bf16 v[126:129], v[152:155], v[184:187], v[126:129]
	v_mfma_f32_16x16x32_bf16 v[122:125], v[160:163], v[184:187], v[122:125]
	v_mfma_f32_16x16x32_bf16 v[118:121], v[152:155], v[192:195], v[118:121]
	v_mfma_f32_16x16x32_bf16 v[114:117], v[160:163], v[192:195], v[114:117]
	v_mfma_f32_16x16x32_bf16 v[94:97], v[152:155], v[200:203], v[94:97]
	v_mfma_f32_16x16x32_bf16 v[90:93], v[160:163], v[200:203], v[90:93]
	v_mfma_f32_16x16x32_bf16 v[86:89], v[152:155], v[208:211], v[86:89]
	v_mfma_f32_16x16x32_bf16 v[82:85], v[160:163], v[208:211], v[82:85]
	v_mfma_f32_16x16x32_bf16 v[126:129], v[156:159], v[188:191], v[126:129]
	v_mfma_f32_16x16x32_bf16 v[122:125], v[164:167], v[188:191], v[122:125]
	v_mfma_f32_16x16x32_bf16 v[118:121], v[156:159], v[196:199], v[118:121]
	v_mfma_f32_16x16x32_bf16 v[114:117], v[164:167], v[196:199], v[114:117]
	v_mfma_f32_16x16x32_bf16 v[94:97], v[156:159], v[204:207], v[94:97]
	v_mfma_f32_16x16x32_bf16 v[90:93], v[164:167], v[204:207], v[90:93]
	v_mfma_f32_16x16x32_bf16 v[86:89], v[156:159], v[212:215], v[86:89]
	v_mfma_f32_16x16x32_bf16 v[82:85], v[164:167], v[212:215], v[82:85]
	s_setprio 0
	s_setprio 1
	v_mfma_f32_16x16x32_bf16 v[110:113], v[168:171], v[184:187], v[110:113]
	v_mfma_f32_16x16x32_bf16 v[106:109], v[176:179], v[184:187], v[106:109]
	v_mfma_f32_16x16x32_bf16 v[102:105], v[168:171], v[192:195], v[102:105]
	v_mfma_f32_16x16x32_bf16 v[98:101], v[176:179], v[192:195], v[98:101]
	v_mfma_f32_16x16x32_bf16 v[78:81], v[168:171], v[200:203], v[78:81]
	v_mfma_f32_16x16x32_bf16 v[74:77], v[176:179], v[200:203], v[74:77]
	v_mfma_f32_16x16x32_bf16 v[70:73], v[168:171], v[208:211], v[70:73]
	v_mfma_f32_16x16x32_bf16 v[66:69], v[176:179], v[208:211], v[66:69]
	v_mfma_f32_16x16x32_bf16 v[110:113], v[172:175], v[188:191], v[110:113]
	v_mfma_f32_16x16x32_bf16 v[106:109], v[180:183], v[188:191], v[106:109]
	v_mfma_f32_16x16x32_bf16 v[102:105], v[172:175], v[196:199], v[102:105]
	v_mfma_f32_16x16x32_bf16 v[98:101], v[180:183], v[196:199], v[98:101]
	v_mfma_f32_16x16x32_bf16 v[78:81], v[172:175], v[204:207], v[78:81]
	v_mfma_f32_16x16x32_bf16 v[74:77], v[180:183], v[204:207], v[74:77]
	v_mfma_f32_16x16x32_bf16 v[70:73], v[172:175], v[212:215], v[70:73]
	v_mfma_f32_16x16x32_bf16 v[66:69], v[180:183], v[212:215], v[66:69]
	s_setprio 0
	s_barrier
	s_add_i32 s36, s68, s48
	v_lshl_add_u64 v[216:217], v[216:217], 0, s[18:19]
	s_mov_b32 m0, s36
	ds_read_b128 v[184:187], v151 offset:49152
	ds_read_b128 v[188:191], v151 offset:50176
	ds_read_b128 v[192:195], v151 offset:51200
	ds_read_b128 v[196:199], v151 offset:52224
	ds_read_b128 v[200:203], v151 offset:53248
	ds_read_b128 v[204:207], v151 offset:54272
	ds_read_b128 v[208:211], v151 offset:55296
	ds_read_b128 v[212:215], v151 offset:56320
	global_load_lds_dwordx4 v[216:217], off
	s_add_i32 m0, s36, 0x2000
	s_add_u32 s34, s34, 0x80080
	v_lshl_add_u64 v[216:217], v[218:219], 0, s[18:19]
	s_addc_u32 s35, s35, 0
	s_add_i32 s36, s69, s48
	global_load_lds_dwordx4 v[216:217], off
	v_lshl_add_u64 v[216:217], s[34:35], 0, v[132:133]
	s_mov_b32 m0, s36
	s_nop 0
	global_load_lds_dwordx4 v[216:217], off
	v_lshl_add_u64 v[216:217], s[34:35], 0, v[136:137]
	s_add_i32 m0, s36, 0x2000
	s_nop 0
	global_load_lds_dwordx4 v[216:217], off
	v_lshl_add_u64 v[216:217], v[220:221], 0, s[18:19]
	s_mov_b32 m0, s60
	s_nop 0
	global_load_lds_dwordx4 v[216:217], off
	v_lshl_add_u64 v[216:217], v[222:223], 0, s[18:19]
	s_mov_b32 m0, s61
	s_nop 0
	global_load_lds_dwordx4 v[216:217], off
	s_waitcnt vmcnt(8)
	s_waitcnt lgkmcnt(0)
	s_barrier
	s_setprio 1
	s_waitcnt lgkmcnt(0)
	v_mfma_f32_16x16x32_bf16 v[62:65], v[152:155], v[184:187], v[62:65]
	v_mfma_f32_16x16x32_bf16 v[58:61], v[160:163], v[184:187], v[58:61]
	v_mfma_f32_16x16x32_bf16 v[54:57], v[152:155], v[192:195], v[54:57]
	v_mfma_f32_16x16x32_bf16 v[50:53], v[160:163], v[192:195], v[50:53]
	v_mfma_f32_16x16x32_bf16 v[30:33], v[152:155], v[200:203], v[30:33]
	v_mfma_f32_16x16x32_bf16 v[26:29], v[160:163], v[200:203], v[26:29]
	v_mfma_f32_16x16x32_bf16 v[22:25], v[152:155], v[208:211], v[22:25]
	v_mfma_f32_16x16x32_bf16 v[18:21], v[160:163], v[208:211], v[18:21]
	v_mfma_f32_16x16x32_bf16 v[62:65], v[156:159], v[188:191], v[62:65]
	v_mfma_f32_16x16x32_bf16 v[58:61], v[164:167], v[188:191], v[58:61]
	v_mfma_f32_16x16x32_bf16 v[54:57], v[156:159], v[196:199], v[54:57]
	v_mfma_f32_16x16x32_bf16 v[50:53], v[164:167], v[196:199], v[50:53]
	v_mfma_f32_16x16x32_bf16 v[30:33], v[156:159], v[204:207], v[30:33]
	v_mfma_f32_16x16x32_bf16 v[26:29], v[164:167], v[204:207], v[26:29]
	v_mfma_f32_16x16x32_bf16 v[22:25], v[156:159], v[212:215], v[22:25]
	v_mfma_f32_16x16x32_bf16 v[18:21], v[164:167], v[212:215], v[18:21]
	s_setprio 0
	s_setprio 1
	v_mfma_f32_16x16x32_bf16 v[46:49], v[168:171], v[184:187], v[46:49]
	v_mfma_f32_16x16x32_bf16 v[42:45], v[176:179], v[184:187], v[42:45]
	v_mfma_f32_16x16x32_bf16 v[38:41], v[168:171], v[192:195], v[38:41]
	v_mfma_f32_16x16x32_bf16 v[34:37], v[176:179], v[192:195], v[34:37]
	v_mfma_f32_16x16x32_bf16 v[14:17], v[168:171], v[200:203], v[14:17]
	v_mfma_f32_16x16x32_bf16 v[10:13], v[176:179], v[200:203], v[10:13]
	v_mfma_f32_16x16x32_bf16 v[6:9], v[168:171], v[208:211], v[6:9]
	v_mfma_f32_16x16x32_bf16 v[2:5], v[176:179], v[208:211], v[2:5]
	v_mfma_f32_16x16x32_bf16 v[46:49], v[172:175], v[188:191], v[46:49]
	v_mfma_f32_16x16x32_bf16 v[42:45], v[180:183], v[188:191], v[42:45]
	v_mfma_f32_16x16x32_bf16 v[38:41], v[172:175], v[196:199], v[38:41]
	v_mfma_f32_16x16x32_bf16 v[34:37], v[180:183], v[196:199], v[34:37]
	v_mfma_f32_16x16x32_bf16 v[14:17], v[172:175], v[204:207], v[14:17]
	v_mfma_f32_16x16x32_bf16 v[10:13], v[180:183], v[204:207], v[10:13]
	v_mfma_f32_16x16x32_bf16 v[6:9], v[172:175], v[212:215], v[6:9]
	v_mfma_f32_16x16x32_bf16 v[2:5], v[180:183], v[212:215], v[2:5]
	s_setprio 0
	s_add_i32 s67, s67, 2
	s_add_u32 s26, s26, 0x100
	s_addc_u32 s27, s27, 0
	s_cmp_gt_u32 s67, 29
	s_barrier
	s_cbranch_scc0 .LBB0_761
	s_add_u32 s26, s21, 0xffffff00
	s_addc_u32 s27, s66, -1
	s_andn2_b64 vcc, exec, s[6:7]
	s_cbranch_vccnz .LBB0_753
	v_mov_b32_e32 v2, 0
	s_mov_b32 s8, s64
	s_mov_b32 s14, s20
	s_mov_b64 s[26:27], s[24:25]
	s_mov_b64 s[16:17], s[22:23]
	s_mov_b32 s59, s65
	v_mov_b32_e32 v3, v2
	v_mov_b32_e32 v4, v2
	v_mov_b32_e32 v5, v2
	v_mov_b32_e32 v6, v2
	v_mov_b32_e32 v7, v2
	v_mov_b32_e32 v8, v2
	v_mov_b32_e32 v9, v2
	v_mov_b32_e32 v10, v2
	v_mov_b32_e32 v11, v2
	v_mov_b32_e32 v12, v2
	v_mov_b32_e32 v13, v2
	v_mov_b32_e32 v14, v2
	v_mov_b32_e32 v15, v2
	v_mov_b32_e32 v16, v2
	v_mov_b32_e32 v17, v2
	v_mov_b32_e32 v34, v2
	v_mov_b32_e32 v35, v2
	v_mov_b32_e32 v36, v2
	v_mov_b32_e32 v37, v2
	v_mov_b32_e32 v38, v2
	v_mov_b32_e32 v39, v2
	v_mov_b32_e32 v40, v2
	v_mov_b32_e32 v41, v2
	v_mov_b32_e32 v42, v2
	v_mov_b32_e32 v43, v2
	v_mov_b32_e32 v44, v2
	v_mov_b32_e32 v45, v2
	v_mov_b32_e32 v46, v2
	v_mov_b32_e32 v47, v2
	v_mov_b32_e32 v48, v2
	v_mov_b32_e32 v49, v2
	v_mov_b32_e32 v18, v2
	v_mov_b32_e32 v19, v2
	v_mov_b32_e32 v20, v2
	v_mov_b32_e32 v21, v2
	v_mov_b32_e32 v22, v2
	v_mov_b32_e32 v23, v2
	v_mov_b32_e32 v24, v2
	v_mov_b32_e32 v25, v2
	v_mov_b32_e32 v26, v2
	v_mov_b32_e32 v27, v2
	v_mov_b32_e32 v28, v2
	v_mov_b32_e32 v29, v2
	v_mov_b32_e32 v30, v2
	v_mov_b32_e32 v31, v2
	v_mov_b32_e32 v32, v2
	v_mov_b32_e32 v33, v2
	v_mov_b32_e32 v50, v2
	v_mov_b32_e32 v51, v2
	v_mov_b32_e32 v52, v2
	v_mov_b32_e32 v53, v2
	v_mov_b32_e32 v54, v2
	v_mov_b32_e32 v55, v2
	v_mov_b32_e32 v56, v2
	v_mov_b32_e32 v57, v2
	v_mov_b32_e32 v58, v2
	v_mov_b32_e32 v59, v2
	v_mov_b32_e32 v60, v2
	v_mov_b32_e32 v61, v2
	v_mov_b32_e32 v62, v2
	v_mov_b32_e32 v63, v2
	v_mov_b32_e32 v64, v2
	v_mov_b32_e32 v65, v2
	v_mov_b32_e32 v66, v2
	v_mov_b32_e32 v67, v2
	v_mov_b32_e32 v68, v2
	v_mov_b32_e32 v69, v2
	v_mov_b32_e32 v70, v2
	v_mov_b32_e32 v71, v2
	v_mov_b32_e32 v72, v2
	v_mov_b32_e32 v73, v2
	v_mov_b32_e32 v74, v2
	v_mov_b32_e32 v75, v2
	v_mov_b32_e32 v76, v2
	v_mov_b32_e32 v77, v2
	v_mov_b32_e32 v78, v2
	v_mov_b32_e32 v79, v2
	v_mov_b32_e32 v80, v2
	v_mov_b32_e32 v81, v2
	v_mov_b32_e32 v98, v2
	v_mov_b32_e32 v99, v2
	v_mov_b32_e32 v100, v2
	v_mov_b32_e32 v101, v2
	v_mov_b32_e32 v102, v2
	v_mov_b32_e32 v103, v2
	v_mov_b32_e32 v104, v2
	v_mov_b32_e32 v105, v2
	v_mov_b32_e32 v106, v2
	v_mov_b32_e32 v107, v2
	v_mov_b32_e32 v108, v2
	v_mov_b32_e32 v109, v2
	v_mov_b32_e32 v110, v2
	v_mov_b32_e32 v111, v2
	v_mov_b32_e32 v112, v2
	v_mov_b32_e32 v113, v2
	v_mov_b32_e32 v82, v2
	v_mov_b32_e32 v83, v2
	v_mov_b32_e32 v84, v2
	v_mov_b32_e32 v85, v2
	v_mov_b32_e32 v86, v2
	v_mov_b32_e32 v87, v2
	v_mov_b32_e32 v88, v2
	v_mov_b32_e32 v89, v2
	v_mov_b32_e32 v90, v2
	v_mov_b32_e32 v91, v2
	v_mov_b32_e32 v92, v2
	v_mov_b32_e32 v93, v2
	v_mov_b32_e32 v94, v2
	v_mov_b32_e32 v95, v2
	v_mov_b32_e32 v96, v2
	v_mov_b32_e32 v97, v2
	v_mov_b32_e32 v114, v2
	v_mov_b32_e32 v115, v2
	v_mov_b32_e32 v116, v2
	v_mov_b32_e32 v117, v2
	v_mov_b32_e32 v118, v2
	v_mov_b32_e32 v119, v2
	v_mov_b32_e32 v120, v2
	v_mov_b32_e32 v121, v2
	v_mov_b32_e32 v122, v2
	v_mov_b32_e32 v123, v2
	v_mov_b32_e32 v124, v2
	v_mov_b32_e32 v125, v2
	v_mov_b32_e32 v126, v2
	v_mov_b32_e32 v127, v2
	v_mov_b32_e32 v128, v2
	v_mov_b32_e32 v129, v2
	s_branch .LBB0_753

.LBB0_965:
	s_cmp_eq_u32 s89, 12
	s_cselect_b64 s[14:15], -1, 0
	s_and_b64 s[14:15], s[14:15], exec
	s_cselect_b32 s15, s54, s88
	s_cselect_b32 s14, s55, s87
	s_add_u32 s90, s12, 0xfffc0080
	s_addc_u32 s91, s13, -1
	s_cmp_eq_u32 s89, 12
	s_cselect_b64 s[42:43], -1, 0
	s_and_b64 s[40:41], s[42:43], exec
	s_cselect_b32 s40, s51, s90
	s_cselect_b32 s41, s50, s91
	s_and_b64 vcc, s[38:39], s[42:43]
	s_and_b64 s[42:43], vcc, exec
	s_cselect_b32 s63, s56, s63
	s_cselect_b32 s64, s86, s64
	s_add_i32 s42, 0, 0x10000
	v_add_u32_e32 v147, s42, v194
	s_add_i32 s43, 0, 0x14000
	ds_read_b128 v[130:133], v147
	ds_read_b128 v[134:137], v147 offset:1024
	ds_read_b128 v[148:151], v147 offset:2048
	ds_read_b128 v[152:155], v147 offset:3072
	v_add_u32_e32 v147, s43, v194
	ds_read_b128 v[156:159], v147
	ds_read_b128 v[160:163], v147 offset:1024
	ds_read_b128 v[164:167], v147 offset:2048
	ds_read_b128 v[168:171], v147 offset:3072
	v_cndmask_b32_e32 v146, v146, v129, vcc
	v_cndmask_b32_e32 v138, v138, v128, vcc
	v_lshl_add_u64 v[228:229], s[12:13], 0, v[144:145]
	s_add_i32 m0, s62, 0xc000
	ds_read_b128 v[196:199], v195
	ds_read_b128 v[200:203], v195 offset:1024
	ds_read_b128 v[204:207], v195 offset:2048
	ds_read_b128 v[208:211], v195 offset:3072
	ds_read_b128 v[212:215], v195 offset:4096
	ds_read_b128 v[216:219], v195 offset:5120
	ds_read_b128 v[220:223], v195 offset:6144
	ds_read_b128 v[224:227], v195 offset:7168
	global_load_lds_dwordx4 v[228:229], off
	v_lshl_add_u64 v[228:229], s[12:13], 0, v[142:143]
	s_add_i32 m0, s62, 0xe000
	s_nop 0
	global_load_lds_dwordx4 v[228:229], off
	s_waitcnt vmcnt(8)
	s_waitcnt lgkmcnt(0)
	s_barrier
	s_setprio 1
	s_waitcnt lgkmcnt(0)
	v_mfma_f32_16x16x32_bf16 v[124:127], v[130:133], v[196:199], v[124:127]
	v_mfma_f32_16x16x32_bf16 v[120:123], v[148:151], v[196:199], v[120:123]
	v_mfma_f32_16x16x32_bf16 v[108:111], v[130:133], v[204:207], v[108:111]
	v_mfma_f32_16x16x32_bf16 v[104:107], v[148:151], v[204:207], v[104:107]
	v_mfma_f32_16x16x32_bf16 v[92:95], v[130:133], v[212:215], v[92:95]
	v_mfma_f32_16x16x32_bf16 v[88:91], v[148:151], v[212:215], v[88:91]
	v_mfma_f32_16x16x32_bf16 v[76:79], v[130:133], v[220:223], v[76:79]
	v_mfma_f32_16x16x32_bf16 v[72:75], v[148:151], v[220:223], v[72:75]
	v_mfma_f32_16x16x32_bf16 v[124:127], v[134:137], v[200:203], v[124:127]
	v_mfma_f32_16x16x32_bf16 v[120:123], v[152:155], v[200:203], v[120:123]
	v_mfma_f32_16x16x32_bf16 v[108:111], v[134:137], v[208:211], v[108:111]
	v_mfma_f32_16x16x32_bf16 v[104:107], v[152:155], v[208:211], v[104:107]
	v_mfma_f32_16x16x32_bf16 v[92:95], v[134:137], v[216:219], v[92:95]
	v_mfma_f32_16x16x32_bf16 v[88:91], v[152:155], v[216:219], v[88:91]
	v_mfma_f32_16x16x32_bf16 v[76:79], v[134:137], v[224:227], v[76:79]
	v_mfma_f32_16x16x32_bf16 v[72:75], v[152:155], v[224:227], v[72:75]
	s_setprio 0
	s_setprio 1
	v_mfma_f32_16x16x32_bf16 v[116:119], v[156:159], v[196:199], v[116:119]
	v_mfma_f32_16x16x32_bf16 v[112:115], v[164:167], v[196:199], v[112:115]
	v_mfma_f32_16x16x32_bf16 v[100:103], v[156:159], v[204:207], v[100:103]
	v_mfma_f32_16x16x32_bf16 v[96:99], v[164:167], v[204:207], v[96:99]
	v_mfma_f32_16x16x32_bf16 v[84:87], v[156:159], v[212:215], v[84:87]
	v_mfma_f32_16x16x32_bf16 v[80:83], v[164:167], v[212:215], v[80:83]
	v_mfma_f32_16x16x32_bf16 v[68:71], v[156:159], v[220:223], v[68:71]
	v_mfma_f32_16x16x32_bf16 v[64:67], v[164:167], v[220:223], v[64:67]
	v_mfma_f32_16x16x32_bf16 v[116:119], v[160:163], v[200:203], v[116:119]
	v_mfma_f32_16x16x32_bf16 v[112:115], v[168:171], v[200:203], v[112:115]
	v_mfma_f32_16x16x32_bf16 v[100:103], v[160:163], v[208:211], v[100:103]
	v_mfma_f32_16x16x32_bf16 v[96:99], v[168:171], v[208:211], v[96:99]
	v_mfma_f32_16x16x32_bf16 v[84:87], v[160:163], v[216:219], v[84:87]
	v_mfma_f32_16x16x32_bf16 v[80:83], v[168:171], v[216:219], v[80:83]
	v_mfma_f32_16x16x32_bf16 v[68:71], v[160:163], v[224:227], v[68:71]
	v_mfma_f32_16x16x32_bf16 v[64:67], v[168:171], v[224:227], v[64:67]
	s_setprio 0
	s_barrier
	s_add_i32 s42, s42, s49
	s_mov_b32 m0, s42
	ds_read_b128 v[196:199], v195 offset:16384
	ds_read_b128 v[200:203], v195 offset:17408
	ds_read_b128 v[204:207], v195 offset:18432
	ds_read_b128 v[208:211], v195 offset:19456
	ds_read_b128 v[212:215], v195 offset:20480
	ds_read_b128 v[216:219], v195 offset:21504
	ds_read_b128 v[220:223], v195 offset:22528
	ds_read_b128 v[224:227], v195 offset:23552
	global_load_lds_dwordx4 v138, s[14:15]
	v_mov_b32_e32 v147, v139
	s_add_i32 m0, s42, 0x2000
	v_lshl_add_u64 v[228:229], s[14:15], 0, v[138:139]
	v_lshl_add_u64 v[230:231], s[14:15], 0, v[146:147]
	global_load_lds_dwordx4 v146, s[14:15]
	s_add_u32 s14, s14, s64
	s_addc_u32 s15, s15, s63
	s_add_i32 s42, s43, s49
	s_mov_b32 m0, s42
	v_lshl_add_u64 v[236:237], s[40:41], 0, v[144:145]
	global_load_lds_dwordx4 v138, s[14:15]
	s_add_i32 m0, s42, 0x2000
	v_lshl_add_u64 v[238:239], s[40:41], 0, v[142:143]
	global_load_lds_dwordx4 v146, s[14:15]
	s_mov_b32 m0, s62
	v_lshl_add_u64 v[232:233], s[14:15], 0, v[138:139]
	global_load_lds_dwordx4 v[236:237], off
	s_mov_b32 m0, s65
	v_lshl_add_u64 v[234:235], s[14:15], 0, v[146:147]
	global_load_lds_dwordx4 v[238:239], off
	s_waitcnt vmcnt(8)
	s_waitcnt lgkmcnt(0)
	s_barrier
	s_setprio 1
	s_waitcnt lgkmcnt(0)
	v_mfma_f32_16x16x32_bf16 v[60:63], v[130:133], v[196:199], v[60:63]
	v_mfma_f32_16x16x32_bf16 v[56:59], v[148:151], v[196:199], v[56:59]
	v_mfma_f32_16x16x32_bf16 v[44:47], v[130:133], v[204:207], v[44:47]
	v_mfma_f32_16x16x32_bf16 v[40:43], v[148:151], v[204:207], v[40:43]
	v_mfma_f32_16x16x32_bf16 v[28:31], v[130:133], v[212:215], v[28:31]
	v_mfma_f32_16x16x32_bf16 v[24:27], v[148:151], v[212:215], v[24:27]
	v_mfma_f32_16x16x32_bf16 v[12:15], v[130:133], v[220:223], v[12:15]
	v_mfma_f32_16x16x32_bf16 v[8:11], v[148:151], v[220:223], v[8:11]
	v_mfma_f32_16x16x32_bf16 v[60:63], v[134:137], v[200:203], v[60:63]
	v_mfma_f32_16x16x32_bf16 v[56:59], v[152:155], v[200:203], v[56:59]
	v_mfma_f32_16x16x32_bf16 v[44:47], v[134:137], v[208:211], v[44:47]
	v_mfma_f32_16x16x32_bf16 v[40:43], v[152:155], v[208:211], v[40:43]
	v_mfma_f32_16x16x32_bf16 v[28:31], v[134:137], v[216:219], v[28:31]
	v_mfma_f32_16x16x32_bf16 v[24:27], v[152:155], v[216:219], v[24:27]
	v_mfma_f32_16x16x32_bf16 v[12:15], v[134:137], v[224:227], v[12:15]
	v_mfma_f32_16x16x32_bf16 v[8:11], v[152:155], v[224:227], v[8:11]
	s_setprio 0
	s_setprio 1
	v_mfma_f32_16x16x32_bf16 v[52:55], v[156:159], v[196:199], v[52:55]
	v_mfma_f32_16x16x32_bf16 v[48:51], v[164:167], v[196:199], v[48:51]
	v_mfma_f32_16x16x32_bf16 v[36:39], v[156:159], v[204:207], v[36:39]
	v_mfma_f32_16x16x32_bf16 v[32:35], v[164:167], v[204:207], v[32:35]
	v_mfma_f32_16x16x32_bf16 v[20:23], v[156:159], v[212:215], v[20:23]
	v_mfma_f32_16x16x32_bf16 v[16:19], v[164:167], v[212:215], v[16:19]
	v_mfma_f32_16x16x32_bf16 v[4:7], v[156:159], v[220:223], v[4:7]
	v_mfma_f32_16x16x32_bf16 v[0:3], v[164:167], v[220:223], v[0:3]
	v_mfma_f32_16x16x32_bf16 v[52:55], v[160:163], v[200:203], v[52:55]
	v_mfma_f32_16x16x32_bf16 v[48:51], v[168:171], v[200:203], v[48:51]
	v_mfma_f32_16x16x32_bf16 v[36:39], v[160:163], v[208:211], v[36:39]
	v_mfma_f32_16x16x32_bf16 v[32:35], v[168:171], v[208:211], v[32:35]
	v_mfma_f32_16x16x32_bf16 v[20:23], v[160:163], v[216:219], v[20:23]
	v_mfma_f32_16x16x32_bf16 v[16:19], v[168:171], v[216:219], v[16:19]
	v_mfma_f32_16x16x32_bf16 v[4:7], v[160:163], v[224:227], v[4:7]
	v_mfma_f32_16x16x32_bf16 v[0:3], v[168:171], v[224:227], v[0:3]
	s_setprio 0
	s_barrier
	s_add_i32 s42, 0, 0x18000
	v_add_u32_e32 v147, s42, v194
	s_add_i32 s43, 0, 0x1c000
	ds_read_b128 v[130:133], v147
	ds_read_b128 v[134:137], v147 offset:1024
	ds_read_b128 v[148:151], v147 offset:2048
	ds_read_b128 v[152:155], v147 offset:3072
	v_add_u32_e32 v147, s43, v194
	ds_read_b128 v[156:159], v147
	ds_read_b128 v[160:163], v147 offset:1024
	ds_read_b128 v[164:167], v147 offset:2048
	ds_read_b128 v[168:171], v147 offset:3072
	s_add_u32 s14, s40, 0x40000
	s_addc_u32 s15, s41, 0
	s_mov_b32 m0, s66
	v_lshl_add_u64 v[240:241], s[14:15], 0, v[144:145]
	ds_read_b128 v[196:199], v195 offset:32768
	ds_read_b128 v[200:203], v195 offset:33792
	ds_read_b128 v[204:207], v195 offset:34816
	ds_read_b128 v[208:211], v195 offset:35840
	ds_read_b128 v[212:215], v195 offset:36864
	ds_read_b128 v[216:219], v195 offset:37888
	ds_read_b128 v[220:223], v195 offset:38912
	ds_read_b128 v[224:227], v195 offset:39936
	global_load_lds_dwordx4 v[240:241], off
	v_lshl_add_u64 v[240:241], s[14:15], 0, v[142:143]
	s_mov_b32 m0, s67
	s_nop 0
	global_load_lds_dwordx4 v[240:241], off
	s_waitcnt vmcnt(8)
	s_waitcnt lgkmcnt(0)
	s_barrier
	s_setprio 1
	s_waitcnt lgkmcnt(0)
	v_mfma_f32_16x16x32_bf16 v[124:127], v[130:133], v[196:199], v[124:127]
	v_mfma_f32_16x16x32_bf16 v[120:123], v[148:151], v[196:199], v[120:123]
	v_mfma_f32_16x16x32_bf16 v[108:111], v[130:133], v[204:207], v[108:111]
	v_mfma_f32_16x16x32_bf16 v[104:107], v[148:151], v[204:207], v[104:107]
	v_mfma_f32_16x16x32_bf16 v[92:95], v[130:133], v[212:215], v[92:95]
	v_mfma_f32_16x16x32_bf16 v[88:91], v[148:151], v[212:215], v[88:91]
	v_mfma_f32_16x16x32_bf16 v[76:79], v[130:133], v[220:223], v[76:79]
	v_mfma_f32_16x16x32_bf16 v[72:75], v[148:151], v[220:223], v[72:75]
	v_mfma_f32_16x16x32_bf16 v[124:127], v[134:137], v[200:203], v[124:127]
	v_mfma_f32_16x16x32_bf16 v[120:123], v[152:155], v[200:203], v[120:123]
	v_mfma_f32_16x16x32_bf16 v[108:111], v[134:137], v[208:211], v[108:111]
	v_mfma_f32_16x16x32_bf16 v[104:107], v[152:155], v[208:211], v[104:107]
	v_mfma_f32_16x16x32_bf16 v[92:95], v[134:137], v[216:219], v[92:95]
	v_mfma_f32_16x16x32_bf16 v[88:91], v[152:155], v[216:219], v[88:91]
	v_mfma_f32_16x16x32_bf16 v[76:79], v[134:137], v[224:227], v[76:79]
	v_mfma_f32_16x16x32_bf16 v[72:75], v[152:155], v[224:227], v[72:75]
	s_setprio 0
	s_setprio 1
	v_mfma_f32_16x16x32_bf16 v[116:119], v[156:159], v[196:199], v[116:119]
	v_mfma_f32_16x16x32_bf16 v[112:115], v[164:167], v[196:199], v[112:115]
	v_mfma_f32_16x16x32_bf16 v[100:103], v[156:159], v[204:207], v[100:103]
	v_mfma_f32_16x16x32_bf16 v[96:99], v[164:167], v[204:207], v[96:99]
	v_mfma_f32_16x16x32_bf16 v[84:87], v[156:159], v[212:215], v[84:87]
	v_mfma_f32_16x16x32_bf16 v[80:83], v[164:167], v[212:215], v[80:83]
	v_mfma_f32_16x16x32_bf16 v[68:71], v[156:159], v[220:223], v[68:71]
	v_mfma_f32_16x16x32_bf16 v[64:67], v[164:167], v[220:223], v[64:67]
	v_mfma_f32_16x16x32_bf16 v[116:119], v[160:163], v[200:203], v[116:119]
	v_mfma_f32_16x16x32_bf16 v[112:115], v[168:171], v[200:203], v[112:115]
	v_mfma_f32_16x16x32_bf16 v[100:103], v[160:163], v[208:211], v[100:103]
	v_mfma_f32_16x16x32_bf16 v[96:99], v[168:171], v[208:211], v[96:99]
	v_mfma_f32_16x16x32_bf16 v[84:87], v[160:163], v[216:219], v[84:87]
	v_mfma_f32_16x16x32_bf16 v[80:83], v[168:171], v[216:219], v[80:83]
	v_mfma_f32_16x16x32_bf16 v[68:71], v[160:163], v[224:227], v[68:71]
	v_mfma_f32_16x16x32_bf16 v[64:67], v[168:171], v[224:227], v[64:67]
	s_setprio 0
	s_barrier
	s_add_i32 s14, s42, s49
	v_lshl_add_u64 v[228:229], v[228:229], 0, s[16:17]
	s_mov_b32 m0, s14
	ds_read_b128 v[196:199], v195 offset:49152
	ds_read_b128 v[200:203], v195 offset:50176
	ds_read_b128 v[204:207], v195 offset:51200
	ds_read_b128 v[208:211], v195 offset:52224
	ds_read_b128 v[212:215], v195 offset:53248
	ds_read_b128 v[216:219], v195 offset:54272
	ds_read_b128 v[220:223], v195 offset:55296
	ds_read_b128 v[224:227], v195 offset:56320
	global_load_lds_dwordx4 v[228:229], off
	v_lshl_add_u64 v[228:229], v[230:231], 0, s[16:17]
	s_add_i32 m0, s14, 0x2000
	s_add_i32 s14, s43, s49
	global_load_lds_dwordx4 v[228:229], off
	v_lshl_add_u64 v[228:229], v[232:233], 0, s[16:17]
	s_mov_b32 m0, s14
	s_nop 0
	global_load_lds_dwordx4 v[228:229], off
	v_lshl_add_u64 v[228:229], v[234:235], 0, s[16:17]
	s_add_i32 m0, s14, 0x2000
	s_nop 0
	global_load_lds_dwordx4 v[228:229], off
	v_lshl_add_u64 v[228:229], v[236:237], 0, s[16:17]
	s_mov_b32 m0, s72
	s_nop 0
	global_load_lds_dwordx4 v[228:229], off
	v_lshl_add_u64 v[228:229], v[238:239], 0, s[16:17]
	s_mov_b32 m0, s73
	s_nop 0
	global_load_lds_dwordx4 v[228:229], off
	s_waitcnt vmcnt(8)
	s_waitcnt lgkmcnt(0)
	s_barrier
	s_setprio 1
	s_waitcnt lgkmcnt(0)
	v_mfma_f32_16x16x32_bf16 v[60:63], v[130:133], v[196:199], v[60:63]
	v_mfma_f32_16x16x32_bf16 v[56:59], v[148:151], v[196:199], v[56:59]
	v_mfma_f32_16x16x32_bf16 v[44:47], v[130:133], v[204:207], v[44:47]
	v_mfma_f32_16x16x32_bf16 v[40:43], v[148:151], v[204:207], v[40:43]
	v_mfma_f32_16x16x32_bf16 v[28:31], v[130:133], v[212:215], v[28:31]
	v_mfma_f32_16x16x32_bf16 v[24:27], v[148:151], v[212:215], v[24:27]
	v_mfma_f32_16x16x32_bf16 v[12:15], v[130:133], v[220:223], v[12:15]
	v_mfma_f32_16x16x32_bf16 v[8:11], v[148:151], v[220:223], v[8:11]
	v_mfma_f32_16x16x32_bf16 v[60:63], v[134:137], v[200:203], v[60:63]
	v_mfma_f32_16x16x32_bf16 v[56:59], v[152:155], v[200:203], v[56:59]
	v_mfma_f32_16x16x32_bf16 v[44:47], v[134:137], v[208:211], v[44:47]
	v_mfma_f32_16x16x32_bf16 v[40:43], v[152:155], v[208:211], v[40:43]
	v_mfma_f32_16x16x32_bf16 v[28:31], v[134:137], v[216:219], v[28:31]
	v_mfma_f32_16x16x32_bf16 v[24:27], v[152:155], v[216:219], v[24:27]
	v_mfma_f32_16x16x32_bf16 v[12:15], v[134:137], v[224:227], v[12:15]
	v_mfma_f32_16x16x32_bf16 v[8:11], v[152:155], v[224:227], v[8:11]
	s_setprio 0
	s_setprio 1
	v_mfma_f32_16x16x32_bf16 v[52:55], v[156:159], v[196:199], v[52:55]
	v_mfma_f32_16x16x32_bf16 v[48:51], v[164:167], v[196:199], v[48:51]
	v_mfma_f32_16x16x32_bf16 v[36:39], v[156:159], v[204:207], v[36:39]
	v_mfma_f32_16x16x32_bf16 v[32:35], v[164:167], v[204:207], v[32:35]
	v_mfma_f32_16x16x32_bf16 v[20:23], v[156:159], v[212:215], v[20:23]
	v_mfma_f32_16x16x32_bf16 v[16:19], v[164:167], v[212:215], v[16:19]
	v_mfma_f32_16x16x32_bf16 v[4:7], v[156:159], v[220:223], v[4:7]
	v_mfma_f32_16x16x32_bf16 v[0:3], v[164:167], v[220:223], v[0:3]
	v_mfma_f32_16x16x32_bf16 v[52:55], v[160:163], v[200:203], v[52:55]
	v_mfma_f32_16x16x32_bf16 v[48:51], v[168:171], v[200:203], v[48:51]
	v_mfma_f32_16x16x32_bf16 v[36:39], v[160:163], v[208:211], v[36:39]
	v_mfma_f32_16x16x32_bf16 v[32:35], v[168:171], v[208:211], v[32:35]
	v_mfma_f32_16x16x32_bf16 v[20:23], v[160:163], v[216:219], v[20:23]
	v_mfma_f32_16x16x32_bf16 v[16:19], v[168:171], v[216:219], v[16:19]
	v_mfma_f32_16x16x32_bf16 v[4:7], v[160:163], v[224:227], v[4:7]
	v_mfma_f32_16x16x32_bf16 v[0:3], v[168:171], v[224:227], v[0:3]
	s_setprio 0
	s_add_i32 s89, s89, 2
	s_add_u32 s12, s12, 0x100
	s_addc_u32 s13, s13, 0
	s_add_u32 s87, s87, 0x100
	s_addc_u32 s88, s88, 0
	s_cmp_gt_u32 s89, 13
	s_barrier
	s_cbranch_scc0 .LBB0_965
	s_and_b64 vcc, exec, s[26:27]
	s_cbranch_vccz .LBB0_968
	s_barrier

.LBB0_1511:
	v_add_u32_e32 v162, s50, v148
	v_add_u32_e32 v178, s51, v148
	s_add_u32 s34, s16, s26
	ds_read_b128 v[150:153], v162
	ds_read_b128 v[154:157], v162 offset:1024
	ds_read_b128 v[158:161], v162 offset:2048
	ds_read_b128 v[162:165], v162 offset:3072
	ds_read_b128 v[166:169], v178
	ds_read_b128 v[170:173], v178 offset:1024
	ds_read_b128 v[174:177], v178 offset:2048
	ds_read_b128 v[178:181], v178 offset:3072
	s_addc_u32 s35, s17, s27
	s_add_u32 s34, s34, 0x100
	s_addc_u32 s35, s35, 0
	s_add_u32 s57, s21, s26
	s_addc_u32 s58, s55, s27
	s_cmpk_eq_i32 s26, 0xf00
	s_cselect_b32 s37, s29, s35
	s_cselect_b32 s36, s28, s34
	s_cselect_b32 s35, s31, s58
	s_cselect_b32 s34, s30, s57
	v_lshl_add_u64 v[214:215], v[144:145], 0, s[26:27]
	s_add_i32 m0, s13, 0xc000
	ds_read_b128 v[182:185], v149
	ds_read_b128 v[186:189], v149 offset:1024
	ds_read_b128 v[190:193], v149 offset:2048
	ds_read_b128 v[194:197], v149 offset:3072
	ds_read_b128 v[198:201], v149 offset:4096
	ds_read_b128 v[202:205], v149 offset:5120
	ds_read_b128 v[206:209], v149 offset:6144
	ds_read_b128 v[210:213], v149 offset:7168
	global_load_lds_dwordx4 v[214:215], off
	v_lshl_add_u64 v[214:215], v[146:147], 0, s[26:27]
	s_add_i32 m0, s13, 0xe000
	s_nop 0
	global_load_lds_dwordx4 v[214:215], off
	s_waitcnt vmcnt(8)
	s_waitcnt lgkmcnt(0)
	s_barrier
	s_setprio 1
	s_waitcnt lgkmcnt(0)
	v_mfma_f32_16x16x32_bf16 v[128:131], v[150:153], v[182:185], v[128:131]
	v_mfma_f32_16x16x32_bf16 v[124:127], v[158:161], v[182:185], v[124:127]
	v_mfma_f32_16x16x32_bf16 v[116:119], v[150:153], v[190:193], v[116:119]
	v_mfma_f32_16x16x32_bf16 v[108:111], v[158:161], v[190:193], v[108:111]
	v_mfma_f32_16x16x32_bf16 v[100:103], v[150:153], v[198:201], v[100:103]
	v_mfma_f32_16x16x32_bf16 v[92:95], v[158:161], v[198:201], v[92:95]
	v_mfma_f32_16x16x32_bf16 v[84:87], v[150:153], v[206:209], v[84:87]
	v_mfma_f32_16x16x32_bf16 v[76:79], v[158:161], v[206:209], v[76:79]
	v_mfma_f32_16x16x32_bf16 v[128:131], v[154:157], v[186:189], v[128:131]
	v_mfma_f32_16x16x32_bf16 v[124:127], v[162:165], v[186:189], v[124:127]
	v_mfma_f32_16x16x32_bf16 v[116:119], v[154:157], v[194:197], v[116:119]
	v_mfma_f32_16x16x32_bf16 v[108:111], v[162:165], v[194:197], v[108:111]
	v_mfma_f32_16x16x32_bf16 v[100:103], v[154:157], v[202:205], v[100:103]
	v_mfma_f32_16x16x32_bf16 v[92:95], v[162:165], v[202:205], v[92:95]
	v_mfma_f32_16x16x32_bf16 v[84:87], v[154:157], v[210:213], v[84:87]
	v_mfma_f32_16x16x32_bf16 v[76:79], v[162:165], v[210:213], v[76:79]
	s_setprio 0
	s_setprio 1
	v_mfma_f32_16x16x32_bf16 v[120:123], v[166:169], v[182:185], v[120:123]
	v_mfma_f32_16x16x32_bf16 v[112:115], v[174:177], v[182:185], v[112:115]
	v_mfma_f32_16x16x32_bf16 v[104:107], v[166:169], v[190:193], v[104:107]
	v_mfma_f32_16x16x32_bf16 v[96:99], v[174:177], v[190:193], v[96:99]
	v_mfma_f32_16x16x32_bf16 v[88:91], v[166:169], v[198:201], v[88:91]
	v_mfma_f32_16x16x32_bf16 v[80:83], v[174:177], v[198:201], v[80:83]
	v_mfma_f32_16x16x32_bf16 v[72:75], v[166:169], v[206:209], v[72:75]
	v_mfma_f32_16x16x32_bf16 v[68:71], v[174:177], v[206:209], v[68:71]
	v_mfma_f32_16x16x32_bf16 v[120:123], v[170:173], v[186:189], v[120:123]
	v_mfma_f32_16x16x32_bf16 v[112:115], v[178:181], v[186:189], v[112:115]
	v_mfma_f32_16x16x32_bf16 v[104:107], v[170:173], v[194:197], v[104:107]
	v_mfma_f32_16x16x32_bf16 v[96:99], v[178:181], v[194:197], v[96:99]
	v_mfma_f32_16x16x32_bf16 v[88:91], v[170:173], v[202:205], v[88:91]
	v_mfma_f32_16x16x32_bf16 v[80:83], v[178:181], v[202:205], v[80:83]
	v_mfma_f32_16x16x32_bf16 v[72:75], v[170:173], v[210:213], v[72:75]
	v_mfma_f32_16x16x32_bf16 v[68:71], v[178:181], v[210:213], v[68:71]
	s_setprio 0
	s_barrier
	s_add_i32 s57, s50, s42
	v_lshl_add_u64 v[214:215], s[34:35], 0, v[2:3]
	s_mov_b32 m0, s57
	ds_read_b128 v[182:185], v149 offset:16384
	ds_read_b128 v[186:189], v149 offset:17408
	ds_read_b128 v[190:193], v149 offset:18432
	ds_read_b128 v[194:197], v149 offset:19456
	ds_read_b128 v[198:201], v149 offset:20480
	ds_read_b128 v[202:205], v149 offset:21504
	ds_read_b128 v[206:209], v149 offset:22528
	ds_read_b128 v[210:213], v149 offset:23552
	global_load_lds_dwordx4 v[214:215], off
	s_add_i32 m0, s57, 0x2000
	s_add_u32 s58, s34, 0x80000
	v_lshl_add_u64 v[216:217], s[34:35], 0, v[134:135]
	s_addc_u32 s59, s35, 0
	s_add_i32 s57, s51, s42
	global_load_lds_dwordx4 v[216:217], off
	v_lshl_add_u64 v[218:219], s[58:59], 0, v[2:3]
	s_mov_b32 m0, s57
	v_lshl_add_u64 v[220:221], s[36:37], 0, v[132:133]
	global_load_lds_dwordx4 v[218:219], off
	v_lshl_add_u64 v[218:219], s[58:59], 0, v[134:135]
	s_add_i32 m0, s57, 0x2000
	s_nop 0
	global_load_lds_dwordx4 v[218:219], off
	v_lshl_add_u64 v[218:219], s[36:37], 0, v[0:1]
	s_mov_b32 m0, s13
	s_nop 0
	global_load_lds_dwordx4 v[218:219], off
	s_mov_b32 m0, s43
	s_nop 0
	global_load_lds_dwordx4 v[220:221], off
	s_waitcnt vmcnt(8)
	s_waitcnt lgkmcnt(0)
	s_barrier
	s_setprio 1
	s_waitcnt lgkmcnt(0)
	v_mfma_f32_16x16x32_bf16 v[64:67], v[150:153], v[182:185], v[64:67]
	v_mfma_f32_16x16x32_bf16 v[60:63], v[158:161], v[182:185], v[60:63]
	v_mfma_f32_16x16x32_bf16 v[52:55], v[150:153], v[190:193], v[52:55]
	v_mfma_f32_16x16x32_bf16 v[44:47], v[158:161], v[190:193], v[44:47]
	v_mfma_f32_16x16x32_bf16 v[36:39], v[150:153], v[198:201], v[36:39]
	v_mfma_f32_16x16x32_bf16 v[28:31], v[158:161], v[198:201], v[28:31]
	v_mfma_f32_16x16x32_bf16 v[20:23], v[150:153], v[206:209], v[20:23]
	v_mfma_f32_16x16x32_bf16 v[12:15], v[158:161], v[206:209], v[12:15]
	v_mfma_f32_16x16x32_bf16 v[64:67], v[154:157], v[186:189], v[64:67]
	v_mfma_f32_16x16x32_bf16 v[60:63], v[162:165], v[186:189], v[60:63]
	v_mfma_f32_16x16x32_bf16 v[52:55], v[154:157], v[194:197], v[52:55]
	v_mfma_f32_16x16x32_bf16 v[44:47], v[162:165], v[194:197], v[44:47]
	v_mfma_f32_16x16x32_bf16 v[36:39], v[154:157], v[202:205], v[36:39]
	v_mfma_f32_16x16x32_bf16 v[28:31], v[162:165], v[202:205], v[28:31]
	v_mfma_f32_16x16x32_bf16 v[20:23], v[154:157], v[210:213], v[20:23]
	v_mfma_f32_16x16x32_bf16 v[12:15], v[162:165], v[210:213], v[12:15]
	s_setprio 0
	s_setprio 1
	v_mfma_f32_16x16x32_bf16 v[56:59], v[166:169], v[182:185], v[56:59]
	v_mfma_f32_16x16x32_bf16 v[48:51], v[174:177], v[182:185], v[48:51]
	v_mfma_f32_16x16x32_bf16 v[40:43], v[166:169], v[190:193], v[40:43]
	v_mfma_f32_16x16x32_bf16 v[32:35], v[174:177], v[190:193], v[32:35]
	v_mfma_f32_16x16x32_bf16 v[24:27], v[166:169], v[198:201], v[24:27]
	v_mfma_f32_16x16x32_bf16 v[16:19], v[174:177], v[198:201], v[16:19]
	v_mfma_f32_16x16x32_bf16 v[8:11], v[166:169], v[206:209], v[8:11]
	v_mfma_f32_16x16x32_bf16 v[4:7], v[174:177], v[206:209], v[4:7]
	v_mfma_f32_16x16x32_bf16 v[56:59], v[170:173], v[186:189], v[56:59]
	v_mfma_f32_16x16x32_bf16 v[48:51], v[178:181], v[186:189], v[48:51]
	v_mfma_f32_16x16x32_bf16 v[40:43], v[170:173], v[194:197], v[40:43]
	v_mfma_f32_16x16x32_bf16 v[32:35], v[178:181], v[194:197], v[32:35]
	v_mfma_f32_16x16x32_bf16 v[24:27], v[170:173], v[202:205], v[24:27]
	v_mfma_f32_16x16x32_bf16 v[16:19], v[178:181], v[202:205], v[16:19]
	v_mfma_f32_16x16x32_bf16 v[8:11], v[170:173], v[210:213], v[8:11]
	v_mfma_f32_16x16x32_bf16 v[4:7], v[178:181], v[210:213], v[4:7]
	s_setprio 0
	s_barrier
	s_add_i32 s57, 0, 0x18000
	s_add_i32 s58, 0, 0x1c000
	v_add_u32_e32 v162, s57, v148
	v_add_u32_e32 v178, s58, v148
	ds_read_b128 v[150:153], v162
	ds_read_b128 v[154:157], v162 offset:1024
	ds_read_b128 v[158:161], v162 offset:2048
	ds_read_b128 v[162:165], v162 offset:3072
	ds_read_b128 v[166:169], v178
	ds_read_b128 v[170:173], v178 offset:1024
	ds_read_b128 v[174:177], v178 offset:2048
	ds_read_b128 v[178:181], v178 offset:3072
	s_add_u32 s36, s36, 0x80000
	s_addc_u32 s37, s37, 0
	s_mov_b32 m0, s45
	v_lshl_add_u64 v[222:223], s[36:37], 0, v[0:1]
	ds_read_b128 v[182:185], v149 offset:32768
	ds_read_b128 v[186:189], v149 offset:33792
	ds_read_b128 v[190:193], v149 offset:34816
	ds_read_b128 v[194:197], v149 offset:35840
	ds_read_b128 v[198:201], v149 offset:36864
	ds_read_b128 v[202:205], v149 offset:37888
	ds_read_b128 v[206:209], v149 offset:38912
	ds_read_b128 v[210:213], v149 offset:39936
	global_load_lds_dwordx4 v[222:223], off
	v_lshl_add_u64 v[222:223], s[36:37], 0, v[132:133]
	s_mov_b32 m0, s46
	s_nop 0
	global_load_lds_dwordx4 v[222:223], off
	s_waitcnt vmcnt(8)
	s_waitcnt lgkmcnt(0)
	s_barrier
	s_setprio 1
	s_waitcnt lgkmcnt(0)
	v_mfma_f32_16x16x32_bf16 v[128:131], v[150:153], v[182:185], v[128:131]
	v_mfma_f32_16x16x32_bf16 v[124:127], v[158:161], v[182:185], v[124:127]
	v_mfma_f32_16x16x32_bf16 v[116:119], v[150:153], v[190:193], v[116:119]
	v_mfma_f32_16x16x32_bf16 v[108:111], v[158:161], v[190:193], v[108:111]
	v_mfma_f32_16x16x32_bf16 v[100:103], v[150:153], v[198:201], v[100:103]
	v_mfma_f32_16x16x32_bf16 v[92:95], v[158:161], v[198:201], v[92:95]
	v_mfma_f32_16x16x32_bf16 v[84:87], v[150:153], v[206:209], v[84:87]
	v_mfma_f32_16x16x32_bf16 v[76:79], v[158:161], v[206:209], v[76:79]
	v_mfma_f32_16x16x32_bf16 v[128:131], v[154:157], v[186:189], v[128:131]
	v_mfma_f32_16x16x32_bf16 v[124:127], v[162:165], v[186:189], v[124:127]
	v_mfma_f32_16x16x32_bf16 v[116:119], v[154:157], v[194:197], v[116:119]
	v_mfma_f32_16x16x32_bf16 v[108:111], v[162:165], v[194:197], v[108:111]
	v_mfma_f32_16x16x32_bf16 v[100:103], v[154:157], v[202:205], v[100:103]
	v_mfma_f32_16x16x32_bf16 v[92:95], v[162:165], v[202:205], v[92:95]
	v_mfma_f32_16x16x32_bf16 v[84:87], v[154:157], v[210:213], v[84:87]
	v_mfma_f32_16x16x32_bf16 v[76:79], v[162:165], v[210:213], v[76:79]
	s_setprio 0
	s_setprio 1
	v_mfma_f32_16x16x32_bf16 v[120:123], v[166:169], v[182:185], v[120:123]
	v_mfma_f32_16x16x32_bf16 v[112:115], v[174:177], v[182:185], v[112:115]
	v_mfma_f32_16x16x32_bf16 v[104:107], v[166:169], v[190:193], v[104:107]
	v_mfma_f32_16x16x32_bf16 v[96:99], v[174:177], v[190:193], v[96:99]
	v_mfma_f32_16x16x32_bf16 v[88:91], v[166:169], v[198:201], v[88:91]
	v_mfma_f32_16x16x32_bf16 v[80:83], v[174:177], v[198:201], v[80:83]
	v_mfma_f32_16x16x32_bf16 v[72:75], v[166:169], v[206:209], v[72:75]
	v_mfma_f32_16x16x32_bf16 v[68:71], v[174:177], v[206:209], v[68:71]
	v_mfma_f32_16x16x32_bf16 v[120:123], v[170:173], v[186:189], v[120:123]
	v_mfma_f32_16x16x32_bf16 v[112:115], v[178:181], v[186:189], v[112:115]
	v_mfma_f32_16x16x32_bf16 v[104:107], v[170:173], v[194:197], v[104:107]
	v_mfma_f32_16x16x32_bf16 v[96:99], v[178:181], v[194:197], v[96:99]
	v_mfma_f32_16x16x32_bf16 v[88:91], v[170:173], v[202:205], v[88:91]
	v_mfma_f32_16x16x32_bf16 v[80:83], v[178:181], v[202:205], v[80:83]
	v_mfma_f32_16x16x32_bf16 v[72:75], v[170:173], v[210:213], v[72:75]
	v_mfma_f32_16x16x32_bf16 v[68:71], v[178:181], v[210:213], v[68:71]
	s_setprio 0
	s_barrier
	s_add_i32 s36, s57, s42
	v_lshl_add_u64 v[214:215], v[214:215], 0, s[18:19]
	s_mov_b32 m0, s36
	ds_read_b128 v[182:185], v149 offset:49152
	ds_read_b128 v[186:189], v149 offset:50176
	ds_read_b128 v[190:193], v149 offset:51200
	ds_read_b128 v[194:197], v149 offset:52224
	ds_read_b128 v[198:201], v149 offset:53248
	ds_read_b128 v[202:205], v149 offset:54272
	ds_read_b128 v[206:209], v149 offset:55296
	ds_read_b128 v[210:213], v149 offset:56320
	global_load_lds_dwordx4 v[214:215], off
	s_add_i32 m0, s36, 0x2000
	s_add_u32 s34, s34, 0x80080
	v_lshl_add_u64 v[214:215], v[216:217], 0, s[18:19]
	s_addc_u32 s35, s35, 0
	s_add_i32 s36, s58, s42
	global_load_lds_dwordx4 v[214:215], off
	v_lshl_add_u64 v[214:215], s[34:35], 0, v[2:3]
	s_mov_b32 m0, s36
	s_nop 0
	global_load_lds_dwordx4 v[214:215], off
	v_lshl_add_u64 v[214:215], s[34:35], 0, v[134:135]
	s_add_i32 m0, s36, 0x2000
	s_nop 0
	global_load_lds_dwordx4 v[214:215], off
	v_lshl_add_u64 v[214:215], v[218:219], 0, s[18:19]
	s_mov_b32 m0, s48
	s_nop 0
	global_load_lds_dwordx4 v[214:215], off
	v_lshl_add_u64 v[214:215], v[220:221], 0, s[18:19]
	s_mov_b32 m0, s49
	s_nop 0
	global_load_lds_dwordx4 v[214:215], off
	s_waitcnt vmcnt(8)
	s_waitcnt lgkmcnt(0)
	s_barrier
	s_setprio 1
	s_waitcnt lgkmcnt(0)
	v_mfma_f32_16x16x32_bf16 v[64:67], v[150:153], v[182:185], v[64:67]
	v_mfma_f32_16x16x32_bf16 v[60:63], v[158:161], v[182:185], v[60:63]
	v_mfma_f32_16x16x32_bf16 v[52:55], v[150:153], v[190:193], v[52:55]
	v_mfma_f32_16x16x32_bf16 v[44:47], v[158:161], v[190:193], v[44:47]
	v_mfma_f32_16x16x32_bf16 v[36:39], v[150:153], v[198:201], v[36:39]
	v_mfma_f32_16x16x32_bf16 v[28:31], v[158:161], v[198:201], v[28:31]
	v_mfma_f32_16x16x32_bf16 v[20:23], v[150:153], v[206:209], v[20:23]
	v_mfma_f32_16x16x32_bf16 v[12:15], v[158:161], v[206:209], v[12:15]
	v_mfma_f32_16x16x32_bf16 v[64:67], v[154:157], v[186:189], v[64:67]
	v_mfma_f32_16x16x32_bf16 v[60:63], v[162:165], v[186:189], v[60:63]
	v_mfma_f32_16x16x32_bf16 v[52:55], v[154:157], v[194:197], v[52:55]
	v_mfma_f32_16x16x32_bf16 v[44:47], v[162:165], v[194:197], v[44:47]
	v_mfma_f32_16x16x32_bf16 v[36:39], v[154:157], v[202:205], v[36:39]
	v_mfma_f32_16x16x32_bf16 v[28:31], v[162:165], v[202:205], v[28:31]
	v_mfma_f32_16x16x32_bf16 v[20:23], v[154:157], v[210:213], v[20:23]
	v_mfma_f32_16x16x32_bf16 v[12:15], v[162:165], v[210:213], v[12:15]
	s_setprio 0
	s_setprio 1
	v_mfma_f32_16x16x32_bf16 v[56:59], v[166:169], v[182:185], v[56:59]
	v_mfma_f32_16x16x32_bf16 v[48:51], v[174:177], v[182:185], v[48:51]
	v_mfma_f32_16x16x32_bf16 v[40:43], v[166:169], v[190:193], v[40:43]
	v_mfma_f32_16x16x32_bf16 v[32:35], v[174:177], v[190:193], v[32:35]
	v_mfma_f32_16x16x32_bf16 v[24:27], v[166:169], v[198:201], v[24:27]
	v_mfma_f32_16x16x32_bf16 v[16:19], v[174:177], v[198:201], v[16:19]
	v_mfma_f32_16x16x32_bf16 v[8:11], v[166:169], v[206:209], v[8:11]
	v_mfma_f32_16x16x32_bf16 v[4:7], v[174:177], v[206:209], v[4:7]
	v_mfma_f32_16x16x32_bf16 v[56:59], v[170:173], v[186:189], v[56:59]
	v_mfma_f32_16x16x32_bf16 v[48:51], v[178:181], v[186:189], v[48:51]
	v_mfma_f32_16x16x32_bf16 v[40:43], v[170:173], v[194:197], v[40:43]
	v_mfma_f32_16x16x32_bf16 v[32:35], v[178:181], v[194:197], v[32:35]
	v_mfma_f32_16x16x32_bf16 v[24:27], v[170:173], v[202:205], v[24:27]
	v_mfma_f32_16x16x32_bf16 v[16:19], v[178:181], v[202:205], v[16:19]
	v_mfma_f32_16x16x32_bf16 v[8:11], v[170:173], v[210:213], v[8:11]
	v_mfma_f32_16x16x32_bf16 v[4:7], v[178:181], v[210:213], v[4:7]
	s_setprio 0
	s_add_i32 s56, s56, 2
	s_add_u32 s26, s26, 0x100
	s_addc_u32 s27, s27, 0
	s_cmp_gt_u32 s56, 29
	s_barrier
	s_cbranch_scc0 .LBB0_1511
	s_add_u32 s26, s21, 0xffffff00
	s_addc_u32 s27, s55, -1
	s_andn2_b64 vcc, exec, s[4:5]
	s_cbranch_vccnz .LBB0_1503
	v_mov_b32_e32 v4, 0
	s_mov_b32 s14, s53
	s_mov_b32 s12, s20
	s_mov_b64 s[26:27], s[24:25]
	s_mov_b64 s[16:17], s[22:23]
	s_mov_b32 s47, s54
	v_mov_b32_e32 v5, v4
	v_mov_b32_e32 v6, v4
	v_mov_b32_e32 v7, v4
	v_mov_b32_e32 v8, v4
	v_mov_b32_e32 v9, v4
	v_mov_b32_e32 v10, v4
	v_mov_b32_e32 v11, v4
	v_mov_b32_e32 v16, v4
	v_mov_b32_e32 v17, v4
	v_mov_b32_e32 v18, v4
	v_mov_b32_e32 v19, v4
	v_mov_b32_e32 v24, v4
	v_mov_b32_e32 v25, v4
	v_mov_b32_e32 v26, v4
	v_mov_b32_e32 v27, v4
	v_mov_b32_e32 v32, v4
	v_mov_b32_e32 v33, v4
	v_mov_b32_e32 v34, v4
	v_mov_b32_e32 v35, v4
	v_mov_b32_e32 v40, v4
	v_mov_b32_e32 v41, v4
	v_mov_b32_e32 v42, v4
	v_mov_b32_e32 v43, v4
	v_mov_b32_e32 v48, v4
	v_mov_b32_e32 v49, v4
	v_mov_b32_e32 v50, v4
	v_mov_b32_e32 v51, v4
	v_mov_b32_e32 v56, v4
	v_mov_b32_e32 v57, v4
	v_mov_b32_e32 v58, v4
	v_mov_b32_e32 v59, v4
	v_mov_b32_e32 v12, v4
	v_mov_b32_e32 v13, v4
	v_mov_b32_e32 v14, v4
	v_mov_b32_e32 v15, v4
	v_mov_b32_e32 v20, v4
	v_mov_b32_e32 v21, v4
	v_mov_b32_e32 v22, v4
	v_mov_b32_e32 v23, v4
	v_mov_b32_e32 v28, v4
	v_mov_b32_e32 v29, v4
	v_mov_b32_e32 v30, v4
	v_mov_b32_e32 v31, v4
	v_mov_b32_e32 v36, v4
	v_mov_b32_e32 v37, v4
	v_mov_b32_e32 v38, v4
	v_mov_b32_e32 v39, v4
	v_mov_b32_e32 v44, v4
	v_mov_b32_e32 v45, v4
	v_mov_b32_e32 v46, v4
	v_mov_b32_e32 v47, v4
	v_mov_b32_e32 v52, v4
	v_mov_b32_e32 v53, v4
	v_mov_b32_e32 v54, v4
	v_mov_b32_e32 v55, v4
	v_mov_b32_e32 v60, v4
	v_mov_b32_e32 v61, v4
	v_mov_b32_e32 v62, v4
	v_mov_b32_e32 v63, v4
	v_mov_b32_e32 v64, v4
	v_mov_b32_e32 v65, v4
	v_mov_b32_e32 v66, v4
	v_mov_b32_e32 v67, v4
	v_mov_b32_e32 v68, v4
	v_mov_b32_e32 v69, v4
	v_mov_b32_e32 v70, v4
	v_mov_b32_e32 v71, v4
	v_mov_b32_e32 v72, v4
	v_mov_b32_e32 v73, v4
	v_mov_b32_e32 v74, v4
	v_mov_b32_e32 v75, v4
	v_mov_b32_e32 v80, v4
	v_mov_b32_e32 v81, v4
	v_mov_b32_e32 v82, v4
	v_mov_b32_e32 v83, v4
	v_mov_b32_e32 v88, v4
	v_mov_b32_e32 v89, v4
	v_mov_b32_e32 v90, v4
	v_mov_b32_e32 v91, v4
	v_mov_b32_e32 v96, v4
	v_mov_b32_e32 v97, v4
	v_mov_b32_e32 v98, v4
	v_mov_b32_e32 v99, v4
	v_mov_b32_e32 v104, v4
	v_mov_b32_e32 v105, v4
	v_mov_b32_e32 v106, v4
	v_mov_b32_e32 v107, v4
	v_mov_b32_e32 v112, v4
	v_mov_b32_e32 v113, v4
	v_mov_b32_e32 v114, v4
	v_mov_b32_e32 v115, v4
	v_mov_b32_e32 v120, v4
	v_mov_b32_e32 v121, v4
	v_mov_b32_e32 v122, v4
	v_mov_b32_e32 v123, v4
	v_mov_b32_e32 v76, v4
	v_mov_b32_e32 v77, v4
	v_mov_b32_e32 v78, v4
	v_mov_b32_e32 v79, v4
	v_mov_b32_e32 v84, v4
	v_mov_b32_e32 v85, v4
	v_mov_b32_e32 v86, v4
	v_mov_b32_e32 v87, v4
	v_mov_b32_e32 v92, v4
	v_mov_b32_e32 v93, v4
	v_mov_b32_e32 v94, v4
	v_mov_b32_e32 v95, v4
	v_mov_b32_e32 v100, v4
	v_mov_b32_e32 v101, v4
	v_mov_b32_e32 v102, v4
	v_mov_b32_e32 v103, v4
	v_mov_b32_e32 v108, v4
	v_mov_b32_e32 v109, v4
	v_mov_b32_e32 v110, v4
	v_mov_b32_e32 v111, v4
	v_mov_b32_e32 v116, v4
	v_mov_b32_e32 v117, v4
	v_mov_b32_e32 v118, v4
	v_mov_b32_e32 v119, v4
	v_mov_b32_e32 v124, v4
	v_mov_b32_e32 v125, v4
	v_mov_b32_e32 v126, v4
	v_mov_b32_e32 v127, v4
	v_mov_b32_e32 v128, v4
	v_mov_b32_e32 v129, v4
	v_mov_b32_e32 v130, v4
	v_mov_b32_e32 v131, v4
	s_branch .LBB0_1503
